# XCD-hierarchical grid barrier: per-XCC arrival counters, one L2 write-back per XCC, per-XCC release generation (bounded sticky spins)
# speedup vs baseline: 1.0686x; 1.0655x over previous
.LBB0_517:
	s_cmp_lt_i32 s24, 2
	s_cselect_b64 s[0:1], -1, 0
	s_xor_b64 s[6:7], s[6:7], -1
	s_or_b64 s[0:1], s[0:1], s[6:7]
	s_and_b64 vcc, exec, s[0:1]
	s_cbranch_vccnz .LBB0_5
	s_cmp_lg_u32 s24, 2
	s_mov_b64 s[6:7], -1
	s_cbranch_scc0 .LBB0_526
	s_waitcnt vmcnt(0) lgkmcnt(0)
	v_readlane_b32 s0, v254, 28
	s_add_i32 s13, s0, 1
	s_waitcnt vmcnt(0)
	s_barrier
	s_mov_b64 s[6:7], exec
	v_readlane_b32 s0, v254, 29
	v_readlane_b32 s1, v254, 30
	s_and_b64 s[0:1], s[6:7], s[0:1]
	s_mov_b64 exec, s[0:1]
	s_cbranch_execz .LBB0_525
	v_readlane_b32 s0, v254, 41
	v_readlane_b32 s1, v254, 42
	s_load_dwordx2 s[0:1], s[0:1], 0x120
	s_getreg_b32 s8, hwreg(HW_REG_XCC_ID, 0, 4)
	s_and_b32 s8, s8, 7
	s_lshr_b32 s9, s54, 3
	v_mov_b32_e32 v1, 1
	s_mul_i32 s9, s9, s13
	s_lshl_b32 s11, s8, 4
	s_lshl_b32 s18, s8, 3
	s_add_u32 s18, s18, 0x80
	v_mov_b32_e32 v3, s11
	v_mov_b32_e32 v5, s18
	s_waitcnt lgkmcnt(0)
	s_add_u32 s0, s0, 0x198000
	s_addc_u32 s1, s1, 0
	global_atomic_add v3, v3, v1, s[0:1] sc0
	s_mov_b32 s20, 0
	s_waitcnt vmcnt(0)
	v_add_u32_e32 v3, 1, v3
	v_cmp_eq_u32_e32 vcc, s9, v3
	s_cbranch_vccz .Lxb_fspin
	buffer_wbl2 sc1
	s_waitcnt vmcnt(0)
	global_atomic_add v3, v2, v1, s[0:1] offset:192 sc0
	s_lshl_b32 s21, s13, 3
	s_waitcnt vmcnt(0)
	v_add_u32_e32 v3, 1, v3
	v_cmp_eq_u32_e32 vcc, s21, v3
	s_cbranch_vccz .Lxb_lspin
	global_atomic_add v2, v1, s[0:1] offset:224
	s_branch .Lxb_lrel
.Lxb_lspin:
	global_load_dword v3, v2, s[0:1] offset:224 sc1
	s_waitcnt vmcnt(0)
	v_cmp_le_u32_e32 vcc, s13, v3
	s_cbranch_vccnz .Lxb_lrel
	s_sleep 1
	s_add_u32 s20, s20, 1
	s_cmp_lt_u32 s20, 0x2000
	s_cbranch_scc1 .Lxb_lspin
	s_branch .Lxb_tmo
.Lxb_lrel:
	buffer_inv sc1
	global_atomic_add v5, v1, s[0:1]
	s_waitcnt vmcnt(0)
	s_branch .Lxb_done
.Lxb_fspin:
	global_load_dword v3, v5, s[0:1] sc1
	s_waitcnt vmcnt(0)
	v_cmp_le_u32_e32 vcc, s13, v3
	s_cbranch_vccnz .Lxb_facq
	s_sleep 1
	s_add_u32 s20, s20, 1
	s_cmp_lt_u32 s20, 0x2000
	s_cbranch_scc1 .Lxb_fspin
.Lxb_tmo:
	v_mov_b32_e32 v1, 0x100000
	global_atomic_add v2, v1, s[0:1] offset:224
	global_atomic_add v2, v1, s[0:1] offset:128
	global_atomic_add v2, v1, s[0:1] offset:136
	global_atomic_add v2, v1, s[0:1] offset:144
	global_atomic_add v2, v1, s[0:1] offset:152
	global_atomic_add v2, v1, s[0:1] offset:160
	global_atomic_add v2, v1, s[0:1] offset:168
	global_atomic_add v2, v1, s[0:1] offset:176
	global_atomic_add v2, v1, s[0:1] offset:184

.Lxb_done:
.LBB0_525:
	s_or_b64 exec, exec, s[6:7]
	s_mov_b64 s[6:7], 0
	s_barrier
